# stack + row-sum chain head merged as one 8-byte VOP3 add (same bytes, one issue slot less per tile)
# speedup vs baseline: 1.0018x; 1.0018x over previous
.Lattn_back_a:
	ds_read_b128 v[126:129], v186 offset:49152
	ds_read_b128 v[130:133], v186 offset:57344
	v_add_f32_e64 v98, v201, v199
	v_add_f32_e32 v98, v202, v98
	v_add_f32_e32 v98, v205, v98
	v_add_f32_e32 v98, v207, v98
	v_add_f32_e32 v98, v209, v98
	s_waitcnt lgkmcnt(1)
	v_mfma_f32_32x32x16_bf16 v[82:97], v[126:129], v[118:121], v[236:251]
	v_add_f32_e32 v98, v211, v98
	v_add_f32_e32 v98, v213, v98
	v_add_f32_e32 v98, v215, v98
	ds_read_b128 v[134:137], v187 offset:49152
	ds_read_b128 v[138:141], v187 offset:57344
	ds_read_b128 v[142:145], v188 offset:49152
	ds_read_b128 v[146:149], v188 offset:57344
	ds_read_b128 v[154:157], v189 offset:49152
	ds_read_b128 v[226:229], v189 offset:57344
	v_add_f32_e32 v98, v216, v98
	v_add_f32_e32 v98, v217, v98
	v_add_f32_e32 v98, v218, v98
	s_waitcnt lgkmcnt(6)
	v_mfma_f32_32x32x16_bf16 v[66:81], v[130:133], v[118:121], v[236:251]
	v_add_f32_e32 v98, v221, v98
	v_add_f32_e32 v98, v222, v98
	v_add_f32_e32 v98, v223, v98
	v_add_f32_e32 v98, v224, v98
	v_add_f32_e32 v98, v195, v98
	v_add_f32_e32 v98, v196, v98
	v_add_f32_e32 v98, v197, v98
	s_waitcnt lgkmcnt(5)
	v_mfma_f32_32x32x16_bf16 v[82:97], v[134:137], v[114:117], v[82:97]
	v_add_f32_e32 v98, v198, v98
	v_add_f32_e32 v98, v200, v98
	v_add_f32_e32 v98, v203, v98
	v_add_f32_e32 v98, v204, v98
	v_add_f32_e32 v98, v206, v98
	v_add_f32_e32 v98, v208, v98
	v_add_f32_e32 v98, v210, v98
	s_waitcnt lgkmcnt(4)
	v_mfma_f32_32x32x16_bf16 v[66:81], v[138:141], v[114:117], v[66:81]
	v_add_f32_e32 v98, v212, v98
	v_add_f32_e32 v98, v214, v98
	v_add_f32_e32 v98, v150, v98
	v_add_f32_e32 v98, v151, v98
	v_add_f32_e32 v98, v152, v98
	v_add_f32_e32 v219, v153, v98
	s_waitcnt lgkmcnt(3)
	v_mfma_f32_32x32x16_bf16 v[82:97], v[142:145], v[110:113], v[82:97]
	v_cvt_pk_bf16_f32 v134, v199, v201
	v_cvt_pk_bf16_f32 v135, v202, v205
	v_cvt_pk_bf16_f32 v136, v207, v209
	v_cvt_pk_bf16_f32 v137, v211, v213
	v_cvt_pk_bf16_f32 v138, v215, v216
	s_waitcnt lgkmcnt(2)
	v_mfma_f32_32x32x16_bf16 v[66:81], v[146:149], v[110:113], v[66:81]
	v_cvt_pk_bf16_f32 v139, v217, v218
	v_cvt_pk_bf16_f32 v140, v221, v222
	v_cvt_pk_bf16_f32 v141, v223, v224
	v_cvt_pk_bf16_f32 v126, v195, v196
	v_cvt_pk_bf16_f32 v127, v197, v198
	v_cvt_pk_bf16_f32 v128, v200, v203
	v_cvt_pk_bf16_f32 v129, v204, v206
	s_waitcnt lgkmcnt(1)
	v_mfma_f32_32x32x16_bf16 v[82:97], v[154:157], v[106:109], v[82:97]
	v_cvt_pk_bf16_f32 v130, v208, v210
	v_cvt_pk_bf16_f32 v131, v212, v214
	v_cvt_pk_bf16_f32 v132, v150, v151
	v_cvt_pk_bf16_f32 v133, v152, v153
	s_waitcnt lgkmcnt(0)
	v_mfma_f32_32x32x16_bf16 v[66:81], v[226:229], v[106:109], v[66:81]
	global_load_dwordx4 v[142:145], v160, s[12:13] offset:2048
	global_load_dwordx4 v[146:149], v252, s[12:13]
	global_load_dwordx4 v[154:157], v161, s[12:13] offset:2048
	s_and_saveexec_b64 s[2:3], s[8:9]
	s_cbranch_execz .LBB0_348
	ds_read2_b32 v[196:197], v194 offset1:1
	ds_read2_b32 v[198:199], v194 offset0:16 offset1:17
	ds_read2_b32 v[200:201], v194 offset0:18 offset1:19
	ds_read2_b32 v[202:203], v194 offset0:24 offset1:25
	ds_read2_b32 v[204:205], v194 offset0:26 offset1:27
	ds_read2_b32 v[206:207], v194 offset0:2 offset1:3
	ds_read2_b32 v[208:209], v194 offset0:8 offset1:9
	ds_read2_b32 v[210:211], v194 offset0:10 offset1:11
	s_waitcnt lgkmcnt(7)
	v_add_f32_e32 v82, v82, v196
	v_add_f32_e32 v83, v83, v197
	s_waitcnt lgkmcnt(3)
	v_add_f32_e32 v96, v96, v204
	v_add_f32_e32 v97, v97, v205
	v_add_f32_e32 v94, v94, v202
	v_add_f32_e32 v95, v95, v203
	v_add_f32_e32 v92, v92, v200
	v_add_f32_e32 v93, v93, v201
	v_add_f32_e32 v90, v90, v198
	v_add_f32_e32 v91, v91, v199
	s_waitcnt lgkmcnt(0)
	v_add_f32_e32 v88, v88, v210
	v_add_f32_e32 v89, v89, v211
	v_add_f32_e32 v86, v86, v208
	v_add_f32_e32 v87, v87, v209
	v_add_f32_e32 v84, v84, v206
	v_add_f32_e32 v85, v85, v207
	ds_read2_b32 v[196:197], v194 offset0:48 offset1:49
	ds_read2_b32 v[198:199], v194 offset0:50 offset1:51
	ds_read2_b32 v[200:201], v194 offset0:56 offset1:57
	ds_read2_b32 v[202:203], v194 offset0:58 offset1:59
	ds_read2_b32 v[204:205], v194 offset0:32 offset1:33
	ds_read2_b32 v[206:207], v194 offset0:34 offset1:35
	ds_read2_b32 v[208:209], v194 offset0:40 offset1:41
	ds_read2_b32 v[210:211], v194 offset0:42 offset1:43
	s_waitcnt lgkmcnt(4)
	v_add_f32_e32 v80, v80, v202
	v_add_f32_e32 v81, v81, v203
	v_add_f32_e32 v78, v78, v200
	v_add_f32_e32 v79, v79, v201
	v_add_f32_e32 v76, v76, v198
	v_add_f32_e32 v77, v77, v199
	v_add_f32_e32 v74, v74, v196
	v_add_f32_e32 v75, v75, v197
	s_waitcnt lgkmcnt(0)
	v_add_f32_e32 v72, v72, v210
	v_add_f32_e32 v73, v73, v211
	v_add_f32_e32 v70, v70, v208
	v_add_f32_e32 v71, v71, v209
	v_add_f32_e32 v68, v68, v206
	v_add_f32_e32 v69, v69, v207
	v_add_f32_e32 v66, v66, v204
	v_add_f32_e32 v67, v67, v205

.Lattn_back_b:
	ds_read_b128 v[126:129], v186 offset:32768
	ds_read_b128 v[130:133], v186 offset:40960
	ds_read_b128 v[134:137], v187 offset:32768
	ds_read_b128 v[138:141], v187 offset:40960
	v_add_f32_e64 v98, v214, v212
	v_add_f32_e32 v98, v216, v98
	v_add_f32_e32 v98, v218, v98
	v_add_f32_e32 v98, v204, v98
	v_add_f32_e32 v98, v206, v98
	v_add_f32_e32 v98, v208, v98
	s_waitcnt lgkmcnt(3)
	v_mfma_f32_32x32x16_bf16 v[82:97], v[126:129], v[118:121], v[236:251]
	v_add_f32_e32 v98, v210, v98
	v_add_f32_e32 v98, v196, v98
	v_add_f32_e32 v98, v198, v98
	v_add_f32_e32 v98, v200, v98
	v_add_f32_e32 v98, v202, v98
	v_add_f32_e32 v98, v222, v98
	v_add_f32_e32 v98, v224, v98
	s_waitcnt lgkmcnt(2)
	v_mfma_f32_32x32x16_bf16 v[66:81], v[130:133], v[118:121], v[236:251]
	v_add_f32_e32 v98, v227, v98
	ds_read_b128 v[126:129], v188 offset:32768
	ds_read_b128 v[142:145], v188 offset:40960
	ds_read_b128 v[146:149], v189 offset:32768
	ds_read_b128 v[154:157], v189 offset:40960
	v_add_f32_e32 v98, v229, v98
	v_add_f32_e32 v98, v213, v98
	v_add_f32_e32 v98, v215, v98
	v_add_f32_e32 v98, v217, v98
	v_add_f32_e32 v98, v221, v98
	s_waitcnt lgkmcnt(5)
	v_mfma_f32_32x32x16_bf16 v[82:97], v[134:137], v[114:117], v[82:97]
	v_add_f32_e32 v98, v205, v98
	v_add_f32_e32 v98, v207, v98
	v_add_f32_e32 v98, v209, v98
	v_add_f32_e32 v98, v211, v98
	v_add_f32_e32 v98, v197, v98
	v_add_f32_e32 v98, v199, v98
	v_add_f32_e32 v98, v201, v98
	s_waitcnt lgkmcnt(4)
	v_mfma_f32_32x32x16_bf16 v[66:81], v[138:141], v[114:117], v[66:81]
	v_add_f32_e32 v98, v203, v98
	v_add_f32_e32 v98, v223, v98
	v_add_f32_e32 v98, v226, v98
	v_add_f32_e32 v98, v228, v98
	v_add_f32_e32 v98, v230, v98
	s_waitcnt lgkmcnt(3)
	v_mfma_f32_32x32x16_bf16 v[82:97], v[126:129], v[110:113], v[82:97]
	v_cvt_pk_bf16_f32 v150, v212, v214
	v_cvt_pk_bf16_f32 v151, v216, v218
	v_cvt_pk_bf16_f32 v152, v204, v206
	v_cvt_pk_bf16_f32 v153, v208, v210
	v_cvt_pk_bf16_f32 v134, v196, v198
	v_cvt_pk_bf16_f32 v135, v200, v202
	v_cvt_pk_bf16_f32 v136, v222, v224
	s_waitcnt lgkmcnt(2)
	v_mfma_f32_32x32x16_bf16 v[66:81], v[142:145], v[110:113], v[66:81]
	v_cvt_pk_bf16_f32 v137, v227, v229
	v_cvt_pk_bf16_f32 v130, v213, v215
	v_cvt_pk_bf16_f32 v131, v217, v221
	v_cvt_pk_bf16_f32 v132, v205, v207
	v_cvt_pk_bf16_f32 v133, v209, v211
	v_cvt_pk_bf16_f32 v126, v197, v199
	v_cvt_pk_bf16_f32 v127, v201, v203
	s_waitcnt lgkmcnt(1)
	v_mfma_f32_32x32x16_bf16 v[82:97], v[146:149], v[106:109], v[82:97]
	v_cvt_pk_bf16_f32 v128, v223, v226
	v_cvt_pk_bf16_f32 v129, v228, v230
	s_waitcnt lgkmcnt(0)
	v_mfma_f32_32x32x16_bf16 v[66:81], v[154:157], v[106:109], v[66:81]
	s_add_u32 s100, s12, 0xa0000
	s_addc_u32 s101, s13, 0
	global_load_dwordx4 v[138:141], v160, s[100:101] offset:2048
	global_load_dwordx4 v[142:145], v252, s[100:101]
	global_load_dwordx4 v[154:157], v161, s[100:101] offset:2048
	s_add_u32 s12, s12, 0x140000
	s_addc_u32 s13, s13, 0
	s_and_saveexec_b64 s[2:3], s[8:9]
	s_cbranch_execz .LBB0_345
	ds_read2_b32 v[196:197], v194 offset0:64 offset1:65
	ds_read2_b32 v[198:199], v194 offset0:80 offset1:81
	ds_read2_b32 v[200:201], v194 offset0:82 offset1:83
	ds_read2_b32 v[202:203], v194 offset0:88 offset1:89
	ds_read2_b32 v[204:205], v194 offset0:90 offset1:91
	ds_read2_b32 v[206:207], v194 offset0:66 offset1:67
	ds_read2_b32 v[208:209], v194 offset0:72 offset1:73
	ds_read2_b32 v[210:211], v194 offset0:74 offset1:75
	s_waitcnt lgkmcnt(7)
	v_add_f32_e32 v82, v82, v196
	v_add_f32_e32 v83, v83, v197
	s_waitcnt lgkmcnt(3)
	v_add_f32_e32 v96, v96, v204
	v_add_f32_e32 v97, v97, v205
	v_add_f32_e32 v94, v94, v202
	v_add_f32_e32 v95, v95, v203
	v_add_f32_e32 v92, v92, v200
	v_add_f32_e32 v93, v93, v201
	v_add_f32_e32 v90, v90, v198
	v_add_f32_e32 v91, v91, v199
	s_waitcnt lgkmcnt(0)
	v_add_f32_e32 v88, v88, v210
	v_add_f32_e32 v89, v89, v211
	v_add_f32_e32 v86, v86, v208
	v_add_f32_e32 v87, v87, v209
	v_add_f32_e32 v84, v84, v206
	v_add_f32_e32 v85, v85, v207
	ds_read2_b32 v[196:197], v194 offset0:112 offset1:113
	ds_read2_b32 v[198:199], v194 offset0:114 offset1:115
	ds_read2_b32 v[200:201], v194 offset0:120 offset1:121
	ds_read2_b32 v[202:203], v194 offset0:122 offset1:123
	ds_read2_b32 v[204:205], v194 offset0:96 offset1:97
	ds_read2_b32 v[206:207], v194 offset0:98 offset1:99
	ds_read2_b32 v[208:209], v194 offset0:104 offset1:105
	ds_read2_b32 v[210:211], v194 offset0:106 offset1:107
	s_waitcnt lgkmcnt(4)
	v_add_f32_e32 v80, v80, v202
	v_add_f32_e32 v81, v81, v203
	v_add_f32_e32 v78, v78, v200
	v_add_f32_e32 v79, v79, v201
	v_add_f32_e32 v76, v76, v198
	v_add_f32_e32 v77, v77, v199
	v_add_f32_e32 v74, v74, v196
	v_add_f32_e32 v75, v75, v197
	s_waitcnt lgkmcnt(0)
	v_add_f32_e32 v72, v72, v210
	v_add_f32_e32 v73, v73, v211
	v_add_f32_e32 v70, v70, v208
	v_add_f32_e32 v71, v71, v209
	v_add_f32_e32 v68, v68, v206
	v_add_f32_e32 v69, v69, v207
	v_add_f32_e32 v66, v66, v204
	v_add_f32_e32 v67, v67, v205
	s_branch .LBB0_345
